# diff_attn item epilogue: subln gain chunk loads prefetched 7 ahead into spare quads, counted vmcnt so stores are never waited on (stacked on v14 best)
# speedup vs baseline: 1.0072x; 1.0072x over previous
; DI void diff_attn_phase(int wv, LAS unsigned char* lds, const bf16_t* qk, const bf16_t* vt, bf16_t* ob, const float* lq1, const float* lk1, const float* lq2, const float* lk2,
;                         const float* subg, int layer_idx) {
;     ...
;         const float lt = l + __shfl_xor(l, 32), inv = 1.f / lt;
;         if (map == 1) { const float f = lam * inv;
; #pragma unroll
;             for (int d = 0; d < 4; ++d)
; #pragma unroll
;                 for (int i = 0; i < 16; ++i) xch[((qsub * 4 + d) * 16 + i) * 64 + lane] = O[d][i] * f; }
;         __syncthreads();
;         if (map == 0) {
;             float ss = 0.f;
; #pragma unroll
;             for (int d = 0; d < 4; ++d)
; #pragma unroll
;                 for (int i = 0; i < 16; ++i) { const float o = O[d][i] * inv - xch[((qsub * 4 + d) * 16 + i) * 64 + lane]; O[d][i] = o; ss += o * o; }
;             ss += __shfl_xor(ss, 32);
;             const float rn = (1.f / sqrtf(ss * (1.f / 128.f) + 1e-6f)) * (1.f - lambda_init);
;             bf16_t* orow = ob + (size_t)(b * SEQ + q0 + rr) * 1024 + hd * 128;
.LBB0_437:
	s_andn2_b64 vcc, exec, s[8:9]
	s_waitcnt lgkmcnt(0)
	s_barrier
	s_cbranch_vccnz .LBB0_419
	ds_read2st64_b32 v[78:79], v215 offset1:1
	ds_read2st64_b32 v[76:77], v215 offset0:2 offset1:3
	ds_read2st64_b32 v[84:85], v215 offset0:4 offset1:5
	ds_read2st64_b32 v[82:83], v215 offset0:6 offset1:7
	ds_read2st64_b32 v[86:87], v215 offset0:8 offset1:9
	ds_read2st64_b32 v[124:125], v215 offset0:10 offset1:11
	ds_read2st64_b32 v[126:127], v215 offset0:12 offset1:13
	ds_read2st64_b32 v[128:129], v215 offset0:14 offset1:15
	ds_read2st64_b32 v[130:131], v215 offset0:16 offset1:17
	ds_read2st64_b32 v[132:133], v215 offset0:18 offset1:19
	ds_read2st64_b32 v[134:135], v215 offset0:20 offset1:21
	ds_read2st64_b32 v[136:137], v215 offset0:22 offset1:23
	ds_read2st64_b32 v[138:139], v215 offset0:24 offset1:25
	ds_read2st64_b32 v[140:141], v215 offset0:26 offset1:27
	ds_read2st64_b32 v[142:143], v215 offset0:28 offset1:29
	ds_read2st64_b32 v[144:145], v215 offset0:30 offset1:31
	ds_read2st64_b32 v[162:163], v215 offset0:32 offset1:33
	ds_read2st64_b32 v[164:165], v215 offset0:34 offset1:35
	ds_read2st64_b32 v[122:123], v215 offset0:36 offset1:37
	ds_read2st64_b32 v[168:169], v215 offset0:38 offset1:39
	ds_read2st64_b32 v[118:119], v215 offset0:40 offset1:41
	ds_read2st64_b32 v[170:171], v215 offset0:42 offset1:43
	ds_read2st64_b32 v[114:115], v215 offset0:44 offset1:45
	ds_read2st64_b32 v[120:121], v215 offset0:46 offset1:47
	ds_read2st64_b32 v[94:95], v215 offset0:48 offset1:49
	ds_read2st64_b32 v[116:117], v215 offset0:50 offset1:51
	ds_read2st64_b32 v[92:93], v215 offset0:52 offset1:53
	ds_read2st64_b32 v[96:97], v215 offset0:54 offset1:55
	ds_read2st64_b32 v[90:91], v215 offset0:56 offset1:57
	ds_read2st64_b32 v[66:67], v215 offset0:58 offset1:59
	v_add_u32_e32 v0, s21, v209
	s_add_i32 s22, s22, s23
	s_waitcnt lgkmcnt(14)
	v_pk_fma_f32 v[80:81], v[50:51], v[70:71], v[78:79] op_sel_hi:[1,0,1] neg_lo:[0,0,1] neg_hi:[0,0,1]
	v_pk_fma_f32 v[76:77], v[52:53], v[70:71], v[76:77] op_sel_hi:[1,0,1] neg_lo:[0,0,1] neg_hi:[0,0,1]
	s_waitcnt lgkmcnt(0)
	v_pk_fma_f32 v[66:67], v[12:13], v[70:71], v[66:67] op_sel_hi:[1,0,1] neg_lo:[0,0,1] neg_hi:[0,0,1]
	ds_read2st64_b32 v[12:13], v215 offset0:60 offset1:61
	v_pk_mul_f32 v[180:181], v[80:81], v[80:81]
	v_readlane_b32 s0, v253, 36
	v_pk_mul_f32 v[178:179], v[76:77], v[76:77]
	v_readlane_b32 s1, v253, 37
	s_waitcnt lgkmcnt(0)
	v_pk_fma_f32 v[68:69], v[14:15], v[70:71], v[12:13] op_sel_hi:[1,0,1] neg_lo:[0,0,1] neg_hi:[0,0,1]
	ds_read_b32 v12, v215 offset:15872
	ds_read_b32 v13, v0
	v_or_b32_e32 v0, s22, v147
	v_pk_fma_f32 v[84:85], v[54:55], v[70:71], v[84:85] op_sel_hi:[1,0,1] neg_lo:[0,0,1] neg_hi:[0,0,1]
	s_lshl_b32 s56, s24, 1
	v_pk_mul_f32 v[182:183], v[84:85], v[84:85]
	s_waitcnt lgkmcnt(0)
	v_pk_fma_f32 v[16:17], v[16:17], v[70:71], v[12:13] op_sel_hi:[1,0,1] neg_lo:[0,0,1] neg_hi:[0,0,1]
	v_lshlrev_b64 v[12:13], 11, v[0:1]
	v_add_f32_e32 v0, v180, v181
	v_add_f32_e32 v0, v0, v178
	v_lshl_add_u64 v[12:13], s[0:1], 0, v[12:13]
	v_add_f32_e32 v0, v0, v179
	v_lshl_add_u64 v[176:177], v[12:13], 0, s[56:57]
	v_mov_b32_e32 v159, v1
	v_pk_fma_f32 v[82:83], v[56:57], v[70:71], v[82:83] op_sel_hi:[1,0,1] neg_lo:[0,0,1] neg_hi:[0,0,1]
	v_add_f32_e32 v0, v0, v182
	v_lshl_add_u64 v[50:51], v[176:177], 0, v[158:159]
	v_pk_mul_f32 v[176:177], v[82:83], v[82:83]
	v_add_f32_e32 v0, v0, v183
	v_pk_fma_f32 v[86:87], v[58:59], v[70:71], v[86:87] op_sel_hi:[1,0,1] neg_lo:[0,0,1] neg_hi:[0,0,1]
	v_add_f32_e32 v0, v0, v176
	v_pk_mul_f32 v[184:185], v[86:87], v[86:87]
	v_add_f32_e32 v0, v0, v177
	v_pk_fma_f32 v[78:79], v[60:61], v[70:71], v[124:125] op_sel_hi:[1,0,1] neg_lo:[0,0,1] neg_hi:[0,0,1]
	v_add_f32_e32 v0, v0, v184
	v_pk_mul_f32 v[124:125], v[78:79], v[78:79]
	v_add_f32_e32 v0, v0, v185
	v_pk_fma_f32 v[62:63], v[62:63], v[70:71], v[126:127] op_sel_hi:[1,0,1] neg_lo:[0,0,1] neg_hi:[0,0,1]
	v_add_f32_e32 v0, v0, v124
	v_pk_mul_f32 v[126:127], v[62:63], v[62:63]
	v_add_f32_e32 v0, v0, v125
	v_pk_fma_f32 v[64:65], v[64:65], v[70:71], v[128:129] op_sel_hi:[1,0,1] neg_lo:[0,0,1] neg_hi:[0,0,1]
	v_add_f32_e32 v0, v0, v126
	v_pk_mul_f32 v[128:129], v[64:65], v[64:65]
	v_add_f32_e32 v0, v0, v127
	v_pk_fma_f32 v[60:61], v[34:35], v[70:71], v[130:131] op_sel_hi:[1,0,1] neg_lo:[0,0,1] neg_hi:[0,0,1]
	v_add_f32_e32 v0, v0, v128
	v_pk_mul_f32 v[130:131], v[60:61], v[60:61]
	v_add_f32_e32 v0, v0, v129
	v_pk_fma_f32 v[58:59], v[36:37], v[70:71], v[132:133] op_sel_hi:[1,0,1] neg_lo:[0,0,1] neg_hi:[0,0,1]
	v_add_f32_e32 v0, v0, v130
	v_pk_mul_f32 v[132:133], v[58:59], v[58:59]
	v_add_f32_e32 v0, v0, v131
	v_pk_fma_f32 v[56:57], v[38:39], v[70:71], v[134:135] op_sel_hi:[1,0,1] neg_lo:[0,0,1] neg_hi:[0,0,1]
	v_add_f32_e32 v0, v0, v132
	v_pk_mul_f32 v[134:135], v[56:57], v[56:57]
	v_add_f32_e32 v0, v0, v133
	v_pk_fma_f32 v[52:53], v[40:41], v[70:71], v[136:137] op_sel_hi:[1,0,1] neg_lo:[0,0,1] neg_hi:[0,0,1]
	v_add_f32_e32 v0, v0, v134
	global_load_dwordx4 v[12:15], v[154:155], off
	global_load_dwordx4 v[186:189], v[154:155], off offset:32
	global_load_dwordx4 v[190:193], v[154:155], off offset:64
	global_load_dwordx4 v[194:197], v[154:155], off offset:96
	global_load_dwordx4 v[198:201], v[154:155], off offset:128
	global_load_dwordx4 v[202:205], v[154:155], off offset:160
	global_load_dwordx4 v[218:221], v[154:155], off offset:192
	global_load_dwordx4 v[222:225], v[154:155], off offset:224
	v_pk_mul_f32 v[136:137], v[52:53], v[52:53]
	v_add_f32_e32 v0, v0, v135
	v_pk_fma_f32 v[54:55], v[42:43], v[70:71], v[138:139] op_sel_hi:[1,0,1] neg_lo:[0,0,1] neg_hi:[0,0,1]
	v_add_f32_e32 v0, v0, v136
	v_pk_mul_f32 v[138:139], v[54:55], v[54:55]
; DI unsigned pk2(float lo, float hi) { f32x2 f = {lo, hi}; bf2_t v = __builtin_convertvector(f, bf2_t); return __builtin_bit_cast(unsigned, v); }
; DI void diff_attn_phase(int wv, LAS unsigned char* lds, const bf16_t* qk, const bf16_t* vt, bf16_t* ob, const float* lq1, const float* lk1, const float* lq2, const float* lk2,
;                         const float* subg, int layer_idx) {
;     ...
;                 for (int i = 0; i < 16; ++i) { const float o = O[d][i] * inv - xch[((qsub * 4 + d) * 16 + i) * 64 + lane]; O[d][i] = o; ss += o * o; }
;             ss += __shfl_xor(ss, 32);
;             const float rn = (1.f / sqrtf(ss * (1.f / 128.f) + 1e-6f)) * (1.f - lambda_init);
;             bf16_t* orow = ob + (size_t)(b * SEQ + q0 + rr) * 1024 + hd * 128;
; #pragma unroll
;             for (int d = 0; d < 4; ++d)
; #pragma unroll
;                 for (int gq = 0; gq < 4; ++gq) { const int dv0 = d * 32 + 8 * gq + 4 * hh; const f32x4 g4 = *(const f32x4*)(subg + dv0);
;                     u32x2 w; w.x = pk2(O[d][4 * gq] * rn * g4.x, O[d][4 * gq + 1] * rn * g4.y); w.y = pk2(O[d][4 * gq + 2] * rn * g4.z, O[d][4 * gq + 3] * rn * g4.w);
;                     *(u32x2*)(orow + dv0) = w; }
	v_add_f32_e32 v0, v0, v137
	v_pk_fma_f32 v[44:45], v[44:45], v[70:71], v[140:141] op_sel_hi:[1,0,1] neg_lo:[0,0,1] neg_hi:[0,0,1]
	v_add_f32_e32 v0, v0, v138
	v_pk_mul_f32 v[140:141], v[44:45], v[44:45]
	v_add_f32_e32 v0, v0, v139
	v_pk_fma_f32 v[46:47], v[46:47], v[70:71], v[142:143] op_sel_hi:[1,0,1] neg_lo:[0,0,1] neg_hi:[0,0,1]
	v_add_f32_e32 v0, v0, v140
	v_pk_mul_f32 v[142:143], v[46:47], v[46:47]
	v_add_f32_e32 v0, v0, v141
	v_pk_fma_f32 v[42:43], v[48:49], v[70:71], v[144:145] op_sel_hi:[1,0,1] neg_lo:[0,0,1] neg_hi:[0,0,1]
	v_add_f32_e32 v0, v0, v142
	v_pk_mul_f32 v[48:49], v[42:43], v[42:43]
	v_add_f32_e32 v0, v0, v143
	v_pk_fma_f32 v[40:41], v[18:19], v[70:71], v[162:163] op_sel_hi:[1,0,1] neg_lo:[0,0,1] neg_hi:[0,0,1]
	v_add_f32_e32 v0, v0, v48
	v_pk_mul_f32 v[162:163], v[40:41], v[40:41]
	v_add_f32_e32 v0, v0, v49
	v_pk_fma_f32 v[38:39], v[20:21], v[70:71], v[164:165] op_sel_hi:[1,0,1] neg_lo:[0,0,1] neg_hi:[0,0,1]
	v_add_f32_e32 v0, v0, v162
	v_pk_mul_f32 v[144:145], v[38:39], v[38:39]
	v_add_f32_e32 v0, v0, v163
	v_pk_fma_f32 v[36:37], v[22:23], v[70:71], v[122:123] op_sel_hi:[1,0,1] neg_lo:[0,0,1] neg_hi:[0,0,1]
	v_add_f32_e32 v0, v0, v144
	v_pk_mul_f32 v[122:123], v[36:37], v[36:37]
	v_add_f32_e32 v0, v0, v145
	v_pk_fma_f32 v[34:35], v[24:25], v[70:71], v[168:169] op_sel_hi:[1,0,1] neg_lo:[0,0,1] neg_hi:[0,0,1]
	v_add_f32_e32 v0, v0, v122
	v_pk_mul_f32 v[164:165], v[34:35], v[34:35]
	v_add_f32_e32 v0, v0, v123
	v_pk_fma_f32 v[24:25], v[28:29], v[70:71], v[170:171] op_sel_hi:[1,0,1] neg_lo:[0,0,1] neg_hi:[0,0,1]
	v_pk_fma_f32 v[28:29], v[26:27], v[70:71], v[118:119] op_sel_hi:[1,0,1] neg_lo:[0,0,1] neg_hi:[0,0,1]
	v_add_f32_e32 v0, v0, v164
	v_pk_mul_f32 v[118:119], v[28:29], v[28:29]
	v_add_f32_e32 v0, v0, v165
	v_add_f32_e32 v0, v0, v118
	v_pk_mul_f32 v[168:169], v[24:25], v[24:25]
	v_add_f32_e32 v0, v0, v119
	v_pk_fma_f32 v[26:27], v[30:31], v[70:71], v[114:115] op_sel_hi:[1,0,1] neg_lo:[0,0,1] neg_hi:[0,0,1]
	v_add_f32_e32 v0, v0, v168
	v_pk_mul_f32 v[30:31], v[26:27], v[26:27]
	v_add_f32_e32 v0, v0, v169
	v_pk_fma_f32 v[22:23], v[32:33], v[70:71], v[120:121] op_sel_hi:[1,0,1] neg_lo:[0,0,1] neg_hi:[0,0,1]
	v_add_f32_e32 v0, v0, v30
	v_pk_mul_f32 v[32:33], v[22:23], v[22:23]
	v_add_f32_e32 v0, v0, v31
	v_pk_fma_f32 v[20:21], v[2:3], v[70:71], v[94:95] op_sel_hi:[1,0,1] neg_lo:[0,0,1] neg_hi:[0,0,1]
	v_add_f32_e32 v0, v0, v32
	v_pk_mul_f32 v[94:95], v[20:21], v[20:21]
	v_add_f32_e32 v0, v0, v33
	v_pk_fma_f32 v[18:19], v[4:5], v[70:71], v[116:117] op_sel_hi:[1,0,1] neg_lo:[0,0,1] neg_hi:[0,0,1]
	v_add_f32_e32 v0, v0, v94
	v_pk_mul_f32 v[114:115], v[18:19], v[18:19]
	v_add_f32_e32 v0, v0, v95
	v_pk_fma_f32 v[6:7], v[6:7], v[70:71], v[92:93] op_sel_hi:[1,0,1] neg_lo:[0,0,1] neg_hi:[0,0,1]
	v_add_f32_e32 v0, v0, v114
	v_pk_mul_f32 v[92:93], v[6:7], v[6:7]
	v_add_f32_e32 v0, v0, v115
	v_pk_fma_f32 v[4:5], v[8:9], v[70:71], v[96:97] op_sel_hi:[1,0,1] neg_lo:[0,0,1] neg_hi:[0,0,1]
	v_add_f32_e32 v0, v0, v92
	v_pk_mul_f32 v[8:9], v[4:5], v[4:5]
	v_add_f32_e32 v0, v0, v93
	v_pk_fma_f32 v[2:3], v[10:11], v[70:71], v[90:91] op_sel_hi:[1,0,1] neg_lo:[0,0,1] neg_hi:[0,0,1]
	v_add_f32_e32 v0, v0, v8
	v_pk_mul_f32 v[10:11], v[2:3], v[2:3]
	v_add_f32_e32 v0, v0, v9
	v_add_f32_e32 v0, v0, v10
	v_pk_mul_f32 v[72:73], v[66:67], v[66:67]
	v_add_f32_e32 v0, v0, v11
	v_add_f32_e32 v0, v0, v72
	v_pk_mul_f32 v[74:75], v[68:69], v[68:69]
	v_add_f32_e32 v0, v0, v73
	v_add_f32_e32 v0, v0, v74
	v_pk_mul_f32 v[88:89], v[16:17], v[16:17]
	v_add_f32_e32 v0, v0, v75
	v_add_f32_e32 v0, v0, v88
	v_add_f32_e32 v0, v0, v89
	ds_bpermute_b32 v8, v238, v0
	s_mov_b32 s0, 0xf800000
	s_waitcnt lgkmcnt(0)
	v_add_f32_e32 v0, v0, v8
	v_fmamk_f32 v0, v0, 0x3c000000, v241
	v_cmp_gt_f32_e32 vcc, s0, v0
	v_mul_f32_e32 v8, 0x4f800000, v0
	s_nop 0
	v_cndmask_b32_e32 v0, v0, v8, vcc
	v_sqrt_f32_e32 v8, v0
	s_nop 0
	v_add_u32_e32 v9, -1, v8
	v_fma_f32 v10, -v9, v8, v0
	v_cmp_ge_f32_e64 s[0:1], 0, v10
	v_add_u32_e32 v10, 1, v8
	s_nop 0
	v_cndmask_b32_e64 v9, v8, v9, s[0:1]
	v_fma_f32 v8, -v10, v8, v0
	v_cmp_lt_f32_e64 s[0:1], 0, v8
	s_nop 1
	v_cndmask_b32_e64 v8, v9, v10, s[0:1]
	v_mul_f32_e32 v9, 0x37800000, v8
	v_cndmask_b32_e32 v8, v8, v9, vcc
	v_cmp_class_f32_e32 vcc, v0, v242
	s_nop 1
	v_cndmask_b32_e32 v0, v8, v0, vcc
	v_div_scale_f32 v8, s[0:1], v0, v0, 1.0
	v_rcp_f32_e32 v9, v8
	s_nop 0
	v_fma_f32 v10, -v8, v9, 1.0
	v_fmac_f32_e32 v9, v10, v9
	v_div_scale_f32 v10, vcc, 1.0, v0, 1.0
	v_mul_f32_e32 v11, v10, v9
	v_fma_f32 v30, -v8, v11, v10
	v_fmac_f32_e32 v11, v30, v9
	v_fma_f32 v8, -v8, v11, v10
	v_div_fmas_f32 v8, v8, v9, v11
	v_div_fixup_f32 v0, v8, v0, 1.0
	v_mul_f32_e32 v0, v210, v0
	v_pk_mul_f32 v[8:9], v[80:81], v[0:1] op_sel_hi:[1,0]
	v_pk_mul_f32 v[10:11], v[76:77], v[0:1] op_sel_hi:[1,0]
	s_waitcnt vmcnt(0)
	v_pk_mul_f32 v[8:9], v[12:13], v[8:9]
	v_pk_mul_f32 v[10:11], v[14:15], v[10:11]
	v_cvt_pk_bf16_f32 v8, v8, v9
	v_cvt_pk_bf16_f32 v9, v10, v11
	global_store_dwordx2 v[50:51], v[8:9], off
	s_nop 0
	v_pk_mul_f32 v[12:13], v[84:85], v[0:1] op_sel_hi:[1,0]
	v_pk_mul_f32 v[6:7], v[6:7], v[0:1] op_sel_hi:[1,0]
	v_pk_mul_f32 v[4:5], v[4:5], v[0:1] op_sel_hi:[1,0]
	v_pk_mul_f32 v[2:3], v[2:3], v[0:1] op_sel_hi:[1,0]
	s_waitcnt vmcnt(7)
	v_mov_b32_e32 v8, v186
	v_mov_b32_e32 v9, v187
	v_mov_b32_e32 v10, v188
	v_mov_b32_e32 v11, v189
	global_load_dwordx4 v[186:189], v[154:155], off offset:256
	v_pk_mul_f32 v[8:9], v[8:9], v[12:13]
	v_pk_mul_f32 v[12:13], v[82:83], v[0:1] op_sel_hi:[1,0]
	v_cvt_pk_bf16_f32 v8, v8, v9
	v_pk_mul_f32 v[10:11], v[10:11], v[12:13]
	v_pk_mul_f32 v[12:13], v[86:87], v[0:1] op_sel_hi:[1,0]
	v_cvt_pk_bf16_f32 v9, v10, v11
	global_store_dwordx2 v[50:51], v[8:9], off offset:16
	s_nop 0
	s_waitcnt vmcnt(8)
; DI unsigned pk2(float lo, float hi) { f32x2 f = {lo, hi}; bf2_t v = __builtin_convertvector(f, bf2_t); return __builtin_bit_cast(unsigned, v); }
; DI void diff_attn_phase(int wv, LAS unsigned char* lds, const bf16_t* qk, const bf16_t* vt, bf16_t* ob, const float* lq1, const float* lk1, const float* lq2, const float* lk2,
;                         const float* subg, int layer_idx) {
;     ...
; #pragma unroll
;             for (int d = 0; d < 4; ++d)
; #pragma unroll
;                 for (int gq = 0; gq < 4; ++gq) { const int dv0 = d * 32 + 8 * gq + 4 * hh; const f32x4 g4 = *(const f32x4*)(subg + dv0);
;                     u32x2 w; w.x = pk2(O[d][4 * gq] * rn * g4.x, O[d][4 * gq + 1] * rn * g4.y); w.y = pk2(O[d][4 * gq + 2] * rn * g4.z, O[d][4 * gq + 3] * rn * g4.w);
;                     *(u32x2*)(orow + dv0) = w; }
	v_mov_b32_e32 v8, v190
	v_mov_b32_e32 v9, v191
	v_mov_b32_e32 v10, v192
	v_mov_b32_e32 v11, v193
	global_load_dwordx4 v[190:193], v[154:155], off offset:288
	v_pk_mul_f32 v[8:9], v[8:9], v[12:13]
	v_pk_mul_f32 v[12:13], v[78:79], v[0:1] op_sel_hi:[1,0]
	v_cvt_pk_bf16_f32 v8, v8, v9
	v_pk_mul_f32 v[10:11], v[10:11], v[12:13]
	v_pk_mul_f32 v[12:13], v[62:63], v[0:1] op_sel_hi:[1,0]
	v_cvt_pk_bf16_f32 v9, v10, v11
	global_store_dwordx2 v[50:51], v[8:9], off offset:32
	s_nop 0
	s_waitcnt vmcnt(9)
	v_mov_b32_e32 v8, v194
	v_mov_b32_e32 v9, v195
	v_mov_b32_e32 v10, v196
	v_mov_b32_e32 v11, v197
	global_load_dwordx4 v[194:197], v[154:155], off offset:320
	v_pk_mul_f32 v[8:9], v[8:9], v[12:13]
	v_pk_mul_f32 v[12:13], v[64:65], v[0:1] op_sel_hi:[1,0]
	v_cvt_pk_bf16_f32 v8, v8, v9
	v_pk_mul_f32 v[10:11], v[10:11], v[12:13]
	v_pk_mul_f32 v[12:13], v[60:61], v[0:1] op_sel_hi:[1,0]
	v_cvt_pk_bf16_f32 v9, v10, v11
	global_store_dwordx2 v[50:51], v[8:9], off offset:48
	s_nop 0
	s_waitcnt vmcnt(10)
	v_mov_b32_e32 v8, v198
	v_mov_b32_e32 v9, v199
	v_mov_b32_e32 v10, v200
	v_mov_b32_e32 v11, v201
	global_load_dwordx4 v[198:201], v[154:155], off offset:352
	v_pk_mul_f32 v[8:9], v[8:9], v[12:13]
	v_pk_mul_f32 v[12:13], v[58:59], v[0:1] op_sel_hi:[1,0]
	v_cvt_pk_bf16_f32 v8, v8, v9
	v_pk_mul_f32 v[10:11], v[10:11], v[12:13]
	v_pk_mul_f32 v[12:13], v[56:57], v[0:1] op_sel_hi:[1,0]
	v_cvt_pk_bf16_f32 v9, v10, v11
	global_store_dwordx2 v[50:51], v[8:9], off offset:64
	s_nop 0
	s_waitcnt vmcnt(11)
	v_mov_b32_e32 v8, v202
	v_mov_b32_e32 v9, v203
	v_mov_b32_e32 v10, v204
	v_mov_b32_e32 v11, v205
	global_load_dwordx4 v[202:205], v[154:155], off offset:384
	v_pk_mul_f32 v[8:9], v[12:13], v[8:9]
	v_pk_mul_f32 v[12:13], v[52:53], v[0:1] op_sel_hi:[1,0]
	v_cvt_pk_bf16_f32 v8, v8, v9
	v_pk_mul_f32 v[10:11], v[12:13], v[10:11]
	v_pk_mul_f32 v[12:13], v[54:55], v[0:1] op_sel_hi:[1,0]
	v_cvt_pk_bf16_f32 v9, v10, v11
	global_store_dwordx2 v[50:51], v[8:9], off offset:80
	s_nop 0
	s_waitcnt vmcnt(12)
	v_mov_b32_e32 v8, v218
	v_mov_b32_e32 v9, v219
	v_mov_b32_e32 v10, v220
	v_mov_b32_e32 v11, v221
	global_load_dwordx4 v[218:221], v[154:155], off offset:416
	v_pk_mul_f32 v[8:9], v[12:13], v[8:9]
	v_pk_mul_f32 v[12:13], v[44:45], v[0:1] op_sel_hi:[1,0]
	v_cvt_pk_bf16_f32 v8, v8, v9
	v_pk_mul_f32 v[10:11], v[12:13], v[10:11]
	v_pk_mul_f32 v[12:13], v[46:47], v[0:1] op_sel_hi:[1,0]
	v_cvt_pk_bf16_f32 v9, v10, v11
	global_store_dwordx2 v[50:51], v[8:9], off offset:96
	s_nop 0
	s_waitcnt vmcnt(13)
	v_mov_b32_e32 v8, v222
	v_mov_b32_e32 v9, v223
	v_mov_b32_e32 v10, v224
	v_mov_b32_e32 v11, v225
	global_load_dwordx4 v[222:225], v[154:155], off offset:448
	v_pk_mul_f32 v[8:9], v[12:13], v[8:9]
	v_pk_mul_f32 v[12:13], v[42:43], v[0:1] op_sel_hi:[1,0]
	v_cvt_pk_bf16_f32 v8, v8, v9
	v_pk_mul_f32 v[10:11], v[12:13], v[10:11]
	v_pk_mul_f32 v[12:13], v[40:41], v[0:1] op_sel_hi:[1,0]
	v_cvt_pk_bf16_f32 v9, v10, v11
	global_store_dwordx2 v[50:51], v[8:9], off offset:112
	s_nop 0
	s_waitcnt vmcnt(13)
	v_mov_b32_e32 v8, v186
	v_mov_b32_e32 v9, v187
	v_mov_b32_e32 v10, v188
	v_mov_b32_e32 v11, v189
	global_load_dwordx4 v[186:189], v[154:155], off offset:480
	v_pk_mul_f32 v[8:9], v[12:13], v[8:9]
	v_pk_mul_f32 v[12:13], v[38:39], v[0:1] op_sel_hi:[1,0]
	v_cvt_pk_bf16_f32 v8, v8, v9
	v_pk_mul_f32 v[10:11], v[12:13], v[10:11]
	v_pk_mul_f32 v[12:13], v[36:37], v[0:1] op_sel_hi:[1,0]
	v_cvt_pk_bf16_f32 v9, v10, v11
	global_store_dwordx2 v[50:51], v[8:9], off offset:128
	s_nop 0
	s_waitcnt vmcnt(13)
	v_mov_b32_e32 v8, v190
	v_mov_b32_e32 v9, v191
	v_mov_b32_e32 v10, v192
	v_mov_b32_e32 v11, v193
	v_pk_mul_f32 v[8:9], v[12:13], v[8:9]
	v_pk_mul_f32 v[12:13], v[34:35], v[0:1] op_sel_hi:[1,0]
	v_cvt_pk_bf16_f32 v8, v8, v9
	v_pk_mul_f32 v[10:11], v[12:13], v[10:11]
	v_pk_mul_f32 v[12:13], v[28:29], v[0:1] op_sel_hi:[1,0]
	v_cvt_pk_bf16_f32 v9, v10, v11
	global_store_dwordx2 v[50:51], v[8:9], off offset:144
	s_nop 0
	s_waitcnt vmcnt(12)
	v_mov_b32_e32 v8, v194
	v_mov_b32_e32 v9, v195
	v_mov_b32_e32 v10, v196
	v_mov_b32_e32 v11, v197
	v_pk_mul_f32 v[8:9], v[12:13], v[8:9]
	v_pk_mul_f32 v[12:13], v[24:25], v[0:1] op_sel_hi:[1,0]
	v_cvt_pk_bf16_f32 v8, v8, v9
	v_pk_mul_f32 v[10:11], v[12:13], v[10:11]
	v_pk_mul_f32 v[12:13], v[26:27], v[0:1] op_sel_hi:[1,0]
	v_cvt_pk_bf16_f32 v9, v10, v11
	global_store_dwordx2 v[50:51], v[8:9], off offset:160
	s_nop 0
	s_waitcnt vmcnt(11)
	v_mov_b32_e32 v8, v198
	v_mov_b32_e32 v9, v199
	v_mov_b32_e32 v10, v200
	v_mov_b32_e32 v11, v201
	v_pk_mul_f32 v[8:9], v[12:13], v[8:9]
	v_pk_mul_f32 v[12:13], v[22:23], v[0:1] op_sel_hi:[1,0]
	v_cvt_pk_bf16_f32 v8, v8, v9
	v_pk_mul_f32 v[10:11], v[12:13], v[10:11]
	v_pk_mul_f32 v[12:13], v[20:21], v[0:1] op_sel_hi:[1,0]
	v_cvt_pk_bf16_f32 v9, v10, v11
	global_store_dwordx2 v[50:51], v[8:9], off offset:176
	s_nop 0
	s_waitcnt vmcnt(10)
	v_mov_b32_e32 v8, v202
	v_mov_b32_e32 v9, v203
	v_mov_b32_e32 v10, v204
	v_mov_b32_e32 v11, v205
	v_pk_mul_f32 v[8:9], v[12:13], v[8:9]
	v_pk_mul_f32 v[12:13], v[18:19], v[0:1] op_sel_hi:[1,0]
	v_cvt_pk_bf16_f32 v8, v8, v9
	v_pk_mul_f32 v[10:11], v[12:13], v[10:11]
	s_nop 0
	v_cvt_pk_bf16_f32 v9, v10, v11
	global_store_dwordx2 v[50:51], v[8:9], off offset:192
	s_nop 0
	s_waitcnt vmcnt(9)
	v_mov_b32_e32 v8, v218
	v_mov_b32_e32 v9, v219
	v_mov_b32_e32 v10, v220
	v_mov_b32_e32 v11, v221
	v_pk_mul_f32 v[6:7], v[6:7], v[8:9]
	v_pk_mul_f32 v[4:5], v[4:5], v[10:11]
	v_cvt_pk_bf16_f32 v6, v6, v7
	v_cvt_pk_bf16_f32 v7, v4, v5
	global_store_dwordx2 v[50:51], v[6:7], off offset:208
	s_nop 0
	s_waitcnt vmcnt(8)
	v_mov_b32_e32 v4, v222
	v_mov_b32_e32 v5, v223
	v_mov_b32_e32 v6, v224
	v_mov_b32_e32 v7, v225
	v_pk_mul_f32 v[2:3], v[2:3], v[4:5]
	v_pk_mul_f32 v[4:5], v[66:67], v[0:1] op_sel_hi:[1,0]
	v_cvt_pk_bf16_f32 v2, v2, v3
	v_pk_mul_f32 v[4:5], v[4:5], v[6:7]
	v_pk_mul_f32 v[6:7], v[68:69], v[0:1] op_sel_hi:[1,0]
	v_cvt_pk_bf16_f32 v3, v4, v5
	global_store_dwordx2 v[50:51], v[2:3], off offset:224
	s_nop 0
	s_waitcnt vmcnt(7)
	v_mov_b32_e32 v2, v186
	v_mov_b32_e32 v3, v187
	v_mov_b32_e32 v4, v188
	v_mov_b32_e32 v5, v189
	v_pk_mul_f32 v[2:3], v[6:7], v[2:3]
	v_pk_mul_f32 v[6:7], v[16:17], v[0:1] op_sel_hi:[1,0]
	v_cvt_pk_bf16_f32 v2, v2, v3
	v_pk_mul_f32 v[4:5], v[6:7], v[4:5]
	s_nop 0
	v_cvt_pk_bf16_f32 v3, v4, v5
	global_store_dwordx2 v[50:51], v[2:3], off offset:240
	s_branch .LBB0_419
